# NA QK fragment reads batched; mLSTM key blocks: LDS reads of block st+1 issued during block st
# speedup vs baseline: 1.0016x; 1.0016x over previous
; DI f32x16 mfma32(bf16x8 a, bf16x8 b, f32x16 c) { return __builtin_amdgcn_mfma_f32_32x32x16_bf16(a, b, c, 0, 0, 0); }
; DI float xmax32(float x) { auto r = __builtin_amdgcn_permlane32_swap(__float_as_uint(x), __float_as_uint(x), false, false); return fmaxf(__uint_as_float(r[0]), __uint_as_float(r[1])); }
; template <int NB>
; DI void softmax_pv(f32x16 (&s)[2], float& mrun, float& lsum, f32x16 (&O)[2], unsigned vaddr) {
;     ...
;   float mx = -1e30f;
; #pragma unroll
;   for (int kb = 0; kb < NB; ++kb)
; #pragma unroll
;     for (int e = 0; e < 16; ++e) mx = fmaxf(mx, s[kb][e]);
;   mx = xmax32(mx);
;   constexpr float THR = 8.f;
;   float alpha = 1.f;
;   if (__builtin_amdgcn_ballot_w64(mx - mrun > THR) != 0ull) {
;     const float mnew = fmaxf(mrun, mx);
;     alpha = __builtin_amdgcn_exp2f((mrun - mnew) * L2E);
;     mrun = mnew;
; #pragma unroll
;     for (int e = 0; e < 16; ++e) { O[0][e] *= alpha; O[1][e] *= alpha; }
;   }
; template <int kind>
; __device__ void attn_job(const Params& p, int layer, int idx, char* smem) {
;     ...
;       f32x16 s[2];
;       __builtin_amdgcn_s_setprio(1);
; #pragma unroll
;       for (int kb = 0; kb < 2; ++kb) {
; #pragma unroll
;         for (int st = 0; st < 4; ++st) s[kb] = mfma32(ld_frag16(Kb + (kb * 32 + tq) * KS_STRIDE + 16 * st + 8 * hh), qf[st], st == 0 ? zero16 : s[kb]);
;       }
;       __builtin_amdgcn_s_setprio(0);
;       softmax_pv<2>(s, mrun, lsum, O, (unsigned)(size_t)Vb + vlane_off);
.LBB0_469:
	s_add_i32 s3, s14, 0x4800
	s_cmp_lt_u32 s13, 4
	s_mov_b64 s[0:1], -1
	s_cbranch_scc0 .LBB0_472
	s_setprio 1
	v_add3_u32 v0, s14, v180, v188
	ds_read_b128 v[2:5], v0
	ds_read_b128 v[6:9], v0 offset:32
	ds_read_b128 v[10:13], v0 offset:64
	ds_read_b128 v[152:155], v0 offset:96
	ds_read_b128 v[156:159], v0 offset:4608
	ds_read_b128 v[160:163], v0 offset:4640
	ds_read_b128 v[164:167], v0 offset:4672
	ds_read_b128 v[168:171], v0 offset:4704
	s_waitcnt lgkmcnt(7)
	v_mfma_f32_32x32x16_bf16 v[112:127], v[2:5], v[136:139], v[16:31]
	s_waitcnt lgkmcnt(6)
	v_mfma_f32_32x32x16_bf16 v[112:127], v[6:9], v[128:131], v[112:127]
	s_waitcnt lgkmcnt(5)
	v_mfma_f32_32x32x16_bf16 v[112:127], v[10:13], v[132:135], v[112:127]
	s_waitcnt lgkmcnt(4)
	v_mfma_f32_32x32x16_bf16 v[112:127], v[152:155], v[140:143], v[112:127]
	s_waitcnt lgkmcnt(3)
	v_mfma_f32_32x32x16_bf16 v[96:111], v[156:159], v[136:139], v[16:31]
	s_waitcnt lgkmcnt(2)
	v_mfma_f32_32x32x16_bf16 v[96:111], v[160:163], v[128:131], v[96:111]
	s_waitcnt lgkmcnt(1)
	v_mfma_f32_32x32x16_bf16 v[96:111], v[164:167], v[132:135], v[96:111]
	s_waitcnt lgkmcnt(0)
	v_mfma_f32_32x32x16_bf16 v[96:111], v[168:171], v[140:143], v[96:111]
	s_setprio 0
	v_add_u32_e32 v0, s3, v181
	ds_read_b64_tr_b16 v[168:169], v0 offset:0
	ds_read_b64_tr_b16 v[170:171], v0 offset:1152
	ds_read_b64_tr_b16 v[164:165], v0 offset:64
	ds_read_b64_tr_b16 v[166:167], v0 offset:1216
	ds_read_b64_tr_b16 v[160:161], v0 offset:2304
	ds_read_b64_tr_b16 v[162:163], v0 offset:3456
	ds_read_b64_tr_b16 v[156:157], v0 offset:2368
	ds_read_b64_tr_b16 v[158:159], v0 offset:3520
	ds_read_b64_tr_b16 v[152:153], v0 offset:4608
	ds_read_b64_tr_b16 v[154:155], v0 offset:5760
	ds_read_b64_tr_b16 v[10:11], v0 offset:4672
	ds_read_b64_tr_b16 v[12:13], v0 offset:5824
	ds_read_b64_tr_b16 v[6:7], v0 offset:6912
	ds_read_b64_tr_b16 v[8:9], v0 offset:8064
	ds_read_b64_tr_b16 v[2:3], v0 offset:6976
	ds_read_b64_tr_b16 v[4:5], v0 offset:8128
	s_waitcnt lgkmcnt(0)
	v_max3_f32 v0, v112, s24, v113
	v_max3_f32 v0, v0, v114, v115
	v_max3_f32 v0, v0, v116, v117
	v_max3_f32 v0, v0, v118, v119
	v_max3_f32 v0, v0, v120, v121
	v_max3_f32 v0, v0, v122, v123
	v_max3_f32 v0, v0, v124, v125
	v_max3_f32 v0, v0, v126, v127
	s_nop 1
	v_max3_f32 v0, v0, v96, v97
	v_max3_f32 v0, v0, v98, v99
	v_max3_f32 v0, v0, v100, v101
	v_max3_f32 v0, v0, v102, v103
	v_max3_f32 v0, v0, v104, v105
	v_max3_f32 v0, v0, v106, v107
	v_max3_f32 v0, v0, v108, v109
	v_max3_f32 v0, v0, v110, v111
	v_mov_b32_e32 v64, v0
	s_nop 1
	v_permlane32_swap_b32_e32 v0, v64
	v_max_f32_e32 v64, v64, v64
	v_max_f32_e32 v0, v0, v0
	v_max_f32_e32 v0, v0, v64
	v_sub_f32_e32 v64, v0, v193
	v_cmp_lt_f32_e32 vcc, s25, v64
	s_cbranch_vccz .LBB0_473
	v_max_f32_e32 v0, v0, v0
	v_max_f32_e32 v64, v193, v193
	v_max_f32_e32 v224, v64, v0
	v_sub_f32_e32 v0, v193, v224
	v_mul_f32_e32 v0, 0x3fb8aa3b, v0
	v_exp_f32_e32 v0, v0
	s_nop 0
	v_pk_mul_f32 v[78:79], v[46:47], v[0:1] op_sel_hi:[1,0]
	v_pk_mul_f32 v[76:77], v[44:45], v[0:1] op_sel_hi:[1,0]
	v_pk_mul_f32 v[74:75], v[42:43], v[0:1] op_sel_hi:[1,0]
	v_pk_mul_f32 v[72:73], v[40:41], v[0:1] op_sel_hi:[1,0]
	v_pk_mul_f32 v[70:71], v[38:39], v[0:1] op_sel_hi:[1,0]
	v_pk_mul_f32 v[68:69], v[36:37], v[0:1] op_sel_hi:[1,0]
	v_pk_mul_f32 v[66:67], v[34:35], v[0:1] op_sel_hi:[1,0]
	v_pk_mul_f32 v[64:65], v[32:33], v[0:1] op_sel_hi:[1,0]
	v_pk_mul_f32 v[94:95], v[62:63], v[0:1] op_sel_hi:[1,0]
	v_pk_mul_f32 v[92:93], v[60:61], v[0:1] op_sel_hi:[1,0]
	v_pk_mul_f32 v[90:91], v[58:59], v[0:1] op_sel_hi:[1,0]
	v_pk_mul_f32 v[88:89], v[56:57], v[0:1] op_sel_hi:[1,0]
	v_pk_mul_f32 v[86:87], v[54:55], v[0:1] op_sel_hi:[1,0]
	v_pk_mul_f32 v[84:85], v[52:53], v[0:1] op_sel_hi:[1,0]
	v_pk_mul_f32 v[82:83], v[50:51], v[0:1] op_sel_hi:[1,0]
	v_pk_mul_f32 v[80:81], v[48:49], v[0:1] op_sel_hi:[1,0]
	s_branch .LBB0_474

; DI f32x16 mfma32(bf16x8 a, bf16x8 b, f32x16 c) { return __builtin_amdgcn_mfma_f32_32x32x16_bf16(a, b, c, 0, 0, 0); }
; DI float xmax32(float x) { auto r = __builtin_amdgcn_permlane32_swap(__float_as_uint(x), __float_as_uint(x), false, false); return fmaxf(__uint_as_float(r[0]), __uint_as_float(r[1])); }
; template <int NB>
; DI void softmax_pv(f32x16 (&s)[2], float& mrun, float& lsum, f32x16 (&O)[2], unsigned vaddr) {
;     ...
;   float mx = -1e30f;
; #pragma unroll
;   for (int kb = 0; kb < NB; ++kb)
; #pragma unroll
;     for (int e = 0; e < 16; ++e) mx = fmaxf(mx, s[kb][e]);
;   mx = xmax32(mx);
;   constexpr float THR = 8.f;
;   float alpha = 1.f;
;   if (__builtin_amdgcn_ballot_w64(mx - mrun > THR) != 0ull) {
;     const float mnew = fmaxf(mrun, mx);
;     alpha = __builtin_amdgcn_exp2f((mrun - mnew) * L2E);
;     mrun = mnew;
; #pragma unroll
;     for (int e = 0; e < 16; ++e) { O[0][e] *= alpha; O[1][e] *= alpha; }
;   }
; template <int kind>
; __device__ void attn_job(const Params& p, int layer, int idx, char* smem) {
;     ...
;     if (kind == 1 && i >= 4) {
;       const int kr = R0 + i - 4;
;       if (kr >= r0A && kr < r0A + 9) {
;         f32x16 s[2];
; #pragma unroll
;         for (int st = 0; st < 4; ++st) s[0] = mfma32(ld_frag16(Kb + (k0 + tq) * KS_STRIDE + 16 * st + 8 * hh), qf[st], st == 0 ? zero16 : s[0]);
;         const bool rowvalid = (kr >= r0l) && (kr < r0l + 8);
;         const unsigned m = rowvalid ? colmask : 0u;
;         const float* brow = rpbs + (kr - qrow_l + 7) * 32 + dcbase;
; #pragma unroll
;         for (int e = 0; e < 16; ++e) {
;           const float bias = brow[(e & 3) + 8 * (e >> 2)];
;           s[0][e] = ((m >> e) & 1u) ? s[0][e] + bias : -1e30f;
;         }
;         softmax_pv<1>(s, mrun, lsum, O, (unsigned)(size_t)Vb + vlane_off + (unsigned)(k0 * KS_STRIDE * 2));
.LBB0_475:
	s_add_i32 s0, s11, s13
	s_cmp_ge_i32 s0, s6
	s_cselect_b64 s[16:17], -1, 0
	s_cmp_lt_i32 s0, s10
	s_cselect_b64 s[20:21], -1, 0
	s_and_b64 s[16:17], s[16:17], s[20:21]
	s_andn2_b64 vcc, exec, s[16:17]
	s_cbranch_vccnz .LBB0_512
	v_add3_u32 v0, s14, v185, v180
	ds_read_b128 v[2:5], v0
	ds_read_b128 v[6:9], v0 offset:32
	ds_read_b128 v[10:13], v0 offset:64
	ds_read_b128 v[80:83], v0 offset:96
	v_cmp_ge_i32_e32 vcc, s0, v184
	v_cmp_lt_i32_e64 s[0:1], s0, v186
	s_and_b64 vcc, vcc, s[0:1]
	v_mov_b32_e32 v15, 0xf149f2ca
	v_mov_b32_e32 v14, 0xf149f2ca
	v_cndmask_b32_e32 v0, 0, v179, vcc
	s_waitcnt lgkmcnt(3)
	v_mfma_f32_32x32x16_bf16 v[64:79], v[2:5], v[136:139], v[16:31]
	s_waitcnt lgkmcnt(2)
	v_mfma_f32_32x32x16_bf16 v[64:79], v[6:9], v[128:131], v[64:79]
	s_waitcnt lgkmcnt(1)
	v_mfma_f32_32x32x16_bf16 v[64:79], v[10:13], v[132:135], v[64:79]
	s_waitcnt lgkmcnt(0)
	v_mfma_f32_32x32x16_bf16 v[64:79], v[80:83], v[140:143], v[64:79]
	ds_read2_b32 v[80:81], v189 offset0:2 offset1:3
	ds_read2_b32 v[82:83], v189 offset0:8 offset1:9
	ds_read2_b32 v[6:7], v189 offset0:16 offset1:17
	ds_read2_b32 v[8:9], v189 offset0:18 offset1:19
	ds_read2_b32 v[10:11], v189 offset0:24 offset1:25
	ds_read2_b32 v[12:13], v189 offset0:26 offset1:27
	ds_read2_b32 v[2:3], v189 offset1:1
	ds_read2_b32 v[4:5], v189 offset0:10 offset1:11
	s_waitcnt lgkmcnt(0)
	s_nop 2
	v_pk_add_f32 v[2:3], v[64:65], v[2:3]
	v_pk_add_f32 v[80:81], v[66:67], v[80:81]
	v_pk_add_f32 v[82:83], v[68:69], v[82:83]
	v_pk_add_f32 v[4:5], v[70:71], v[4:5]
	v_pk_add_f32 v[6:7], v[72:73], v[6:7]
	v_pk_add_f32 v[8:9], v[74:75], v[8:9]
	v_pk_add_f32 v[10:11], v[76:77], v[10:11]
	v_pk_add_f32 v[12:13], v[78:79], v[12:13]
	v_bfe_i32 v64, v0, 0, 1
	v_bfe_i32 v65, v0, 1, 1
	v_bfe_i32 v66, v0, 2, 1
	v_bfe_i32 v67, v0, 3, 1
	v_bfi_b32 v14, v64, v2, s24
	v_bfi_b32 v15, v65, v3, s24
	v_bfi_b32 v80, v66, v80, s24
	v_bfi_b32 v81, v67, v81, s24
	v_bfe_i32 v64, v0, 4, 1
	v_bfe_i32 v65, v0, 5, 1
	v_bfe_i32 v66, v0, 6, 1
	v_bfe_i32 v67, v0, 7, 1
	v_bfi_b32 v82, v64, v82, s24
	v_bfi_b32 v83, v65, v83, s24
	v_bfi_b32 v68, v66, v4, s24
	v_bfi_b32 v69, v67, v5, s24
	v_bfe_i32 v64, v0, 8, 1
	v_bfe_i32 v65, v0, 9, 1
	v_bfe_i32 v66, v0, 10, 1
	v_bfe_i32 v67, v0, 11, 1
	v_bfi_b32 v70, v64, v6, s24
	v_bfi_b32 v71, v65, v7, s24
	v_bfi_b32 v72, v66, v8, s24
	v_bfi_b32 v73, v67, v9, s24
	v_bfe_i32 v64, v0, 12, 1
	v_bfe_i32 v65, v0, 13, 1
	v_bfe_i32 v66, v0, 14, 1
	v_bfe_i32 v67, v0, 15, 1
	v_bfi_b32 v74, v64, v10, s24
	v_bfi_b32 v75, v65, v11, s24
	v_bfi_b32 v76, v66, v12, s24
	v_bfi_b32 v77, v67, v13, s24
	v_add_u32_e32 v0, s3, v187
	ds_read_b64_tr_b16 v[64:65], v0 offset:0
	ds_read_b64_tr_b16 v[66:67], v0 offset:1152
	ds_read_b64_tr_b16 v[10:11], v0 offset:64
	ds_read_b64_tr_b16 v[12:13], v0 offset:1216
	ds_read_b64_tr_b16 v[6:7], v0 offset:2304
	ds_read_b64_tr_b16 v[8:9], v0 offset:3456
	ds_read_b64_tr_b16 v[2:3], v0 offset:2368
	ds_read_b64_tr_b16 v[4:5], v0 offset:3520
	s_waitcnt lgkmcnt(0)
	v_max3_f32 v0, v14, s24, v15
	v_max3_f32 v0, v0, v80, v81
	v_max3_f32 v0, v0, v82, v83
	v_max3_f32 v0, v0, v68, v69
	v_max3_f32 v0, v0, v70, v71
	v_max3_f32 v0, v0, v72, v73
	v_max3_f32 v0, v0, v74, v75
	v_max3_f32 v0, v0, v76, v77
	v_mov_b32_e32 v78, v0
	s_nop 1
	v_permlane32_swap_b32_e32 v0, v78
	v_max_f32_e32 v78, v78, v78
	v_max_f32_e32 v0, v0, v0
	v_max_f32_e32 v0, v0, v78
	v_sub_f32_e32 v78, v0, v193
	v_cmp_lt_f32_e32 vcc, s25, v78
	s_cbranch_vccz .LBB0_510
	v_max_f32_e32 v0, v0, v0
	v_max_f32_e32 v78, v193, v193
	v_max_f32_e32 v78, v78, v0
	v_sub_f32_e32 v0, v193, v78
	v_mul_f32_e32 v0, 0x3fb8aa3b, v0
	v_exp_f32_e32 v0, v0
	v_mov_b32_e32 v193, v78
	v_pk_mul_f32 v[46:47], v[46:47], v[0:1] op_sel_hi:[1,0]
	v_pk_mul_f32 v[44:45], v[44:45], v[0:1] op_sel_hi:[1,0]
	v_pk_mul_f32 v[42:43], v[42:43], v[0:1] op_sel_hi:[1,0]
	v_pk_mul_f32 v[40:41], v[40:41], v[0:1] op_sel_hi:[1,0]
	v_pk_mul_f32 v[38:39], v[38:39], v[0:1] op_sel_hi:[1,0]
	v_pk_mul_f32 v[36:37], v[36:37], v[0:1] op_sel_hi:[1,0]
	v_pk_mul_f32 v[34:35], v[34:35], v[0:1] op_sel_hi:[1,0]
	v_pk_mul_f32 v[32:33], v[32:33], v[0:1] op_sel_hi:[1,0]
	v_pk_mul_f32 v[62:63], v[62:63], v[0:1] op_sel_hi:[1,0]
	v_pk_mul_f32 v[60:61], v[60:61], v[0:1] op_sel_hi:[1,0]
	v_pk_mul_f32 v[58:59], v[58:59], v[0:1] op_sel_hi:[1,0]
	v_pk_mul_f32 v[56:57], v[56:57], v[0:1] op_sel_hi:[1,0]
	v_pk_mul_f32 v[54:55], v[54:55], v[0:1] op_sel_hi:[1,0]
	v_pk_mul_f32 v[52:53], v[52:53], v[0:1] op_sel_hi:[1,0]
	v_pk_mul_f32 v[50:51], v[50:51], v[0:1] op_sel_hi:[1,0]
	v_pk_mul_f32 v[48:49], v[48:49], v[0:1] op_sel_hi:[1,0]
	s_branch .LBB0_511

; DI f32x4 mfma16(bf16x8 a, bf16x8 b, f32x4 c) { return __builtin_amdgcn_mfma_f32_16x16x32_bf16(a, b, c, 0, 0, 0); }
; __device__ void mlstm_chain(const Params& p, int layer, int idx, char* smem) {
;     ...
;     if (i + 1 < 36) {
;       const int nb = chunk_base(i + 1);
;       const size_t ro = (size_t)(nb + (dir ? 63 - lrow : lrow)) * ZW;
;       nq = *(const u32x4*)(Z + ro + MQ + h * 64 + c8 * 8);
;       nk = *(const u32x4*)(Z + ro + MK + h * 64 + c8 * 8);
;       nv = *(const u32x4*)(Z + ro + MV + h * 64 + c8 * 8);
;     }
;     {
;       const int tb = (w < 4) ? w : 7 - w, vh = w >> 2;
;       const int t = tb * 16 + c;
;       const float Mt = fmaxf(mprev, cms[t]);
;       const float win = __expf(mprev - Mt);
;       bf16x8 qf[2];
; #pragma unroll
;       for (int kk = 0; kk < 2; ++kk) qf[kk] = ld_frag16(Qs + t * 72 + 32 * kk + 8 * g);
;       float psum = 0.f;
;       unsigned pp[4][2];
; #pragma unroll
;       for (int st = 0; st < 4; ++st) {
;         f32x4 sacc = (f32x4){0.f, 0.f, 0.f, 0.f};
;         if (st <= tb) {
; #pragma unroll
;           for (int kk = 0; kk < 2; ++kk) sacc = mfma16(ld_frag16(Ksm + (st * 16 + c) * 72 + 32 * kk + 8 * g), qf[kk], sacc);
; #pragma unroll
;           for (int rg = 0; rg < 4; ++rg) {
;             const int s = st * 16 + 4 * g + rg;
;             const float dv = (s <= t) ? __expf(us[s] - Mt) : 0.f;
;             sacc[rg] *= dv;
;             psum += sacc[rg];
;           }
;         }
;         pp[st][0] = pk_bf16(sacc[0], sacc[1]);
;         pp[st][1] = pk_bf16(sacc[2], sacc[3]);
;       }
.LBB0_553:
	s_lshl_b32 s17, s74, 6
	s_add_i32 s17, s17, s16
	v_add_u32_e32 v10, s17, v60
	v_mad_i64_i32 v[14:15], s[16:17], v10, s79, v[38:39]
	global_load_dwordx4 v[18:21], v[14:15], off offset:2560
	global_load_dwordx4 v[10:13], v[14:15], off offset:3072
	s_nop 0
	global_load_dwordx4 v[14:17], v[14:15], off offset:3584
	v_add_u32_e32 v53, s29, v65
	ds_read_b32 v22, v53 offset:18432
	v_add3_u32 v70, s73, v56, v49
	v_add_u32_e32 v30, s72, v49
	v_cndmask_b32_e64 v31, 0, 1, s[8:9]
	v_cmp_ne_u32_e64 s[72:73], 1, v31
	s_waitcnt lgkmcnt(0)
	v_max_f32_e32 v22, v22, v22
	v_max_f32_e32 v41, v0, v22
	ds_read_b128 v[26:29], v70
	ds_read_b128 v[22:25], v70 offset:64
	v_mov_b32_e32 v0, 0
	s_andn2_b64 vcc, exec, s[8:9]
	v_add_u32_e32 v75, v30, v59
	v_mov_b32_e32 v73, 0
	v_mov_b32_e32 v72, 0
	v_mov_b32_e32 v71, 0
	v_mov_b32_e32 v74, 0
	s_cbranch_vccnz .LBB0_563
	v_add_u32_e32 v204, s29, v66
	v_mov_b32_e32 v226, v75
	ds_read_b32 v200, v204 offset:54272
	ds_read_b32 v201, v204 offset:54276
	ds_read_b32 v202, v204 offset:54280
	ds_read_b32 v203, v204 offset:54284
	ds_read_b128 v[206:209], v226
	ds_read_b128 v[210:213], v226 offset:64
	s_waitcnt lgkmcnt(2)
	v_sub_f32_e32 v200, v200, v41
	v_sub_f32_e32 v201, v201, v41
	v_sub_f32_e32 v202, v202, v41
	v_sub_f32_e32 v203, v203, v41
	v_mul_f32_e32 v200, 0x3fb8aa3b, v200
	v_mul_f32_e32 v201, 0x3fb8aa3b, v201
	v_mul_f32_e32 v202, 0x3fb8aa3b, v202
	v_mul_f32_e32 v203, 0x3fb8aa3b, v203
	v_exp_f32_e32 v200, v200
	v_exp_f32_e32 v201, v201
	v_exp_f32_e32 v202, v202
	v_exp_f32_e32 v203, v203
	s_waitcnt lgkmcnt(1)
	v_mfma_f32_16x16x32_bf16 v[30:33], v[206:209], v[26:29], 0
	s_waitcnt lgkmcnt(0)
	v_mfma_f32_16x16x32_bf16 v[30:33], v[210:213], v[22:25], v[30:33]
	ds_read_b32 v214, v204 offset:54336
	ds_read_b32 v215, v204 offset:54340
	ds_read_b32 v216, v204 offset:54344
	ds_read_b32 v217, v204 offset:54348
	ds_read_b128 v[218:221], v226 offset:2304
	ds_read_b128 v[222:225], v226 offset:2368
	v_cndmask_b32_e64 v72, 0, v200, s[70:71]
	v_cndmask_b32_e64 v73, 0, v201, s[68:69]
	v_cndmask_b32_e64 v0, 0, v202, s[66:67]
	v_cndmask_b32_e64 v76, 0, v203, s[64:65]
	s_nop 4
	v_fma_f32 v74, v30, v72, 0
	v_fmac_f32_e32 v74, v31, v73
	v_fmac_f32_e32 v74, v32, v0
	v_mul_f32_e32 v71, v30, v72
	v_mul_f32_e32 v72, v31, v73
	v_mul_f32_e32 v73, v32, v0
	v_mul_f32_e32 v0, v33, v76
	v_fmac_f32_e32 v74, v33, v76
.LBB0_563:
	v_cndmask_b32_e64 v30, 0, 1, s[10:11]
	v_cmp_ne_u32_e64 s[74:75], 1, v30
	s_andn2_b64 vcc, exec, s[10:11]
	v_mov_b32_e32 v77, 0
	s_cbranch_vccnz .LBB0_568
	s_waitcnt lgkmcnt(2)
	v_sub_f32_e32 v214, v214, v41
	v_sub_f32_e32 v215, v215, v41
	v_sub_f32_e32 v216, v216, v41
	v_sub_f32_e32 v217, v217, v41
	v_mul_f32_e32 v214, 0x3fb8aa3b, v214
	v_mul_f32_e32 v215, 0x3fb8aa3b, v215
	v_mul_f32_e32 v216, 0x3fb8aa3b, v216
	v_mul_f32_e32 v217, 0x3fb8aa3b, v217
	v_exp_f32_e32 v214, v214
	v_exp_f32_e32 v215, v215
	v_exp_f32_e32 v216, v216
	v_exp_f32_e32 v217, v217
	s_waitcnt lgkmcnt(1)
	v_mfma_f32_16x16x32_bf16 v[30:33], v[218:221], v[26:29], 0
	s_waitcnt lgkmcnt(0)
	v_mfma_f32_16x16x32_bf16 v[30:33], v[222:225], v[22:25], v[30:33]
	ds_read_b32 v200, v204 offset:54400
	ds_read_b32 v201, v204 offset:54404
	ds_read_b32 v202, v204 offset:54408
	ds_read_b32 v203, v204 offset:54412
	ds_read_b128 v[206:209], v226 offset:4608
	ds_read_b128 v[210:213], v226 offset:4672
	v_cndmask_b32_e64 v78, 0, v214, s[62:63]
	v_cndmask_b32_e64 v79, 0, v215, s[60:61]
	v_cndmask_b32_e64 v77, 0, v216, s[58:59]
	v_cndmask_b32_e64 v80, 0, v217, s[56:57]
	s_nop 4
	v_fmac_f32_e32 v74, v30, v78
	v_fmac_f32_e32 v74, v31, v79
	v_fmac_f32_e32 v74, v32, v77
	v_mul_f32_e32 v76, v30, v78
	v_mul_f32_e32 v78, v31, v79
	v_mul_f32_e32 v79, v32, v77
	v_mul_f32_e32 v77, v33, v80
	v_fmac_f32_e32 v74, v33, v80
.LBB0_574:
	v_cndmask_b32_e64 v30, 0, 1, s[12:13]
	v_cmp_ne_u32_e64 s[76:77], 1, v30
	s_andn2_b64 vcc, exec, s[12:13]
	v_mov_b32_e32 v81, 0
	s_cbranch_vccnz .LBB0_579
	s_waitcnt lgkmcnt(2)
	v_sub_f32_e32 v200, v200, v41
	v_sub_f32_e32 v201, v201, v41
	v_sub_f32_e32 v202, v202, v41
	v_sub_f32_e32 v203, v203, v41
	v_mul_f32_e32 v200, 0x3fb8aa3b, v200
	v_mul_f32_e32 v201, 0x3fb8aa3b, v201
	v_mul_f32_e32 v202, 0x3fb8aa3b, v202
	v_mul_f32_e32 v203, 0x3fb8aa3b, v203
	v_exp_f32_e32 v200, v200
	v_exp_f32_e32 v201, v201
	v_exp_f32_e32 v202, v202
	v_exp_f32_e32 v203, v203
	s_waitcnt lgkmcnt(1)
	v_mfma_f32_16x16x32_bf16 v[30:33], v[206:209], v[26:29], 0
	s_waitcnt lgkmcnt(0)
	v_mfma_f32_16x16x32_bf16 v[30:33], v[210:213], v[22:25], v[30:33]
	ds_read_b32 v214, v204 offset:54464
	ds_read_b32 v215, v204 offset:54468
	ds_read_b32 v216, v204 offset:54472
	ds_read_b32 v217, v204 offset:54476
	ds_read_b128 v[218:221], v226 offset:6912
	ds_read_b128 v[222:225], v226 offset:6976
	v_cndmask_b32_e64 v82, 0, v200, s[54:55]
	v_cndmask_b32_e64 v83, 0, v201, s[52:53]
	v_cndmask_b32_e64 v81, 0, v202, s[50:51]
	v_cndmask_b32_e64 v84, 0, v203, s[48:49]
	s_nop 4
	v_fmac_f32_e32 v74, v30, v82
	v_fmac_f32_e32 v74, v31, v83
	v_fmac_f32_e32 v74, v32, v81
	v_mul_f32_e32 v80, v30, v82
	v_mul_f32_e32 v82, v31, v83
	v_mul_f32_e32 v83, v32, v81
	v_mul_f32_e32 v81, v33, v84
	v_fmac_f32_e32 v74, v33, v84
	s_mov_b64 s[16:17], -1
	s_and_b64 vcc, exec, s[6:7]
	s_cbranch_vccz .LBB0_594
.LBB0_585:
	s_waitcnt lgkmcnt(2)
	v_sub_f32_e32 v214, v214, v41
	v_sub_f32_e32 v215, v215, v41
	v_sub_f32_e32 v216, v216, v41
	v_sub_f32_e32 v217, v217, v41
	v_mul_f32_e32 v214, 0x3fb8aa3b, v214
	v_mul_f32_e32 v215, 0x3fb8aa3b, v215
	v_mul_f32_e32 v216, 0x3fb8aa3b, v216
	v_mul_f32_e32 v217, 0x3fb8aa3b, v217
	v_exp_f32_e32 v214, v214
	v_exp_f32_e32 v215, v215
	v_exp_f32_e32 v216, v216
	v_exp_f32_e32 v217, v217
	s_waitcnt lgkmcnt(1)
	v_mfma_f32_16x16x32_bf16 v[30:33], v[218:221], v[26:29], 0
	s_waitcnt lgkmcnt(0)
	v_mfma_f32_16x16x32_bf16 v[30:33], v[222:225], v[22:25], v[30:33]
	v_cndmask_b32_e64 v85, 0, v214, s[46:47]
	v_cndmask_b32_e64 v86, 0, v215, s[44:45]
	v_cndmask_b32_e64 v75, 0, v216, s[42:43]
	v_cndmask_b32_e64 v87, 0, v217, s[40:41]
	s_nop 4
	v_mul_f32_e32 v84, v30, v85
	v_fma_f32 v30, v30, v85, v74
	v_fmac_f32_e32 v30, v31, v86
	v_fmac_f32_e32 v30, v32, v75
	v_mul_f32_e32 v85, v31, v86
	v_mul_f32_e32 v31, v32, v75
	v_mul_f32_e32 v32, v33, v87
	v_fmac_f32_e32 v30, v33, v87
	s_mov_b64 s[16:17], 0
